# mix-weight copy WM stored fragment-major (8 full lines per B-fragment load instead of 32 partial lines)
# speedup vs baseline: 1.0126x; 1.0091x over previous
.LBB0_6:
	s_or_b64 exec, exec, s[2:3]
	s_add_u32 s4, s76, 0x200000
	s_addc_u32 s5, s77, 0
	s_load_dwordx16 s[8:23], s[0:1], 0x40
	s_add_u32 s0, s76, 0x900000
	s_addc_u32 s1, s77, 0
	s_add_u32 s78, s76, 0x2000000
	s_addc_u32 s79, s77, 0
	v_writelane_b32 v247, s0, 5
	s_add_u32 s96, s76, 0x4100000
	s_addc_u32 s97, s77, 0
	v_writelane_b32 v247, s1, 6
	s_lshr_b32 s0, s46, 6
	s_cmp_lt_i32 s52, 1
	v_writelane_b32 v247, s0, 7
	s_cselect_b64 s[0:1], -1, 0
	s_cmp_gt_i32 s53, 0
	s_cselect_b64 s[2:3], -1, 0
	s_and_b64 s[2:3], s[0:1], s[2:3]
	s_andn2_b64 vcc, exec, s[2:3]
	v_and_b32_e32 v194, 63, v0
	s_cbranch_vccnz .LBB0_45
	s_lshl_b32 s0, s63, 3
	v_readlane_b32 s1, v247, 7
	s_add_i32 s0, s0, s1
	s_lshl_b32 s30, s33, 3
	s_cmpk_gt_i32 s0, 0x69f
	s_cbranch_scc1 .LBB0_14
	v_readlane_b32 s1, v247, 7
	s_lshl_b32 s1, s1, 14
	v_lshlrev_b32_e32 v2, 3, v0
	s_add_i32 s1, s1, 0
	v_lshrrev_b32_e32 v1, 5, v194
	v_and_b32_e32 v8, 31, v0
	v_lshrrev_b32_e32 v9, 3, v194
	v_and_b32_e32 v2, 56, v2
	v_lshl_add_u32 v14, v8, 2, s1
	v_mul_u32_u24_e32 v15, 0x84, v1
	v_mul_u32_u24_e32 v6, 0x84, v2
	v_readlane_b32 s24, v247, 5
	v_lshlrev_b32_e32 v7, 2, v9
	v_lshlrev_b32_e32 v2, 1, v2
	v_mov_b32_e32 v3, 0
	v_readlane_b32 s25, v247, 6
	v_add3_u32 v10, s1, v6, v7
	s_lshl_b32 s1, s0, 5
	s_lshl_b32 s6, s0, 2
	v_add_u32_e32 v14, v14, v15
	s_mov_b32 s7, 0
	v_and_b32_e32 v4, 16, v2
	v_and_b32_e32 v5, 0x60, v2
	v_lshlrev_b32_e32 v4, 8, v4
	v_lshl_or_b32 v4, v5, 4, v4
	v_mov_b32_e32 v5, 0
	v_lshl_add_u64 v[4:5], s[24:25], 0, v[4:5]
	v_or_b32_e32 v11, 8, v9
	v_or_b32_e32 v12, 16, v9
	v_or_b32_e32 v13, 24, v9
	v_lshl_add_u64 v[6:7], s[4:5], 0, v[2:3]
	s_addk_i32 s1, 0xfb00
	s_lshl_b32 s26, s30, 5
	s_add_i32 s27, s6, 0xffffe600
	s_lshl_b32 s28, s30, 2
	s_movk_i32 s29, 0x1000
	s_movk_i32 s31, 0x2000
	s_movk_i32 s34, 0x3000
	s_movk_i32 s35, 0x4000
	s_movk_i32 s36, 0x5000
	s_movk_i32 s37, 0x6000
	s_movk_i32 s38, 0x7000
	s_movk_i32 s39, 0x4ff
	s_movk_i32 s40, 0x900
	s_movk_i32 s41, 0x3400
	v_mov_b32_e32 v15, 0x7f
	v_add_u32_e32 v16, 0x400, v14
	v_add_u32_e32 v17, 0x800, v14
	v_add_u32_e32 v18, 0xc00, v14
	v_add_u32_e32 v19, 0x1000, v14
	v_add_u32_e32 v20, 0x1400, v14
	v_add_u32_e32 v21, 0x1800, v14
	v_add_u32_e32 v22, 0x1c00, v14
	s_mov_b32 s42, s0
	s_branch .LBB0_10

.LBB0_10:
	s_cmpk_gt_i32 s42, 0x67f
	s_mov_b64 s[24:25], -1
	s_cbranch_scc0 .LBB0_12
	s_add_i32 s25, s1, 0xffff3500
	s_and_b32 s24, s25, 0x1e0
	s_and_b32 s25, s25, 0x180
	s_and_b32 s6, s27, 64
	v_or_b32_e32 v2, s25, v1
	v_or_b32_e32 v26, s6, v2
	v_bitop3_b32 v2, s24, v15, v8 bitop3:0xc8
	v_or_b32_e32 v23, s24, v8
	v_lshlrev_b32_e32 v2, 2, v2
	s_waitcnt lgkmcnt(0)
	v_lshl_add_u64 v[24:25], s[12:13], 0, v[2:3]
	v_lshlrev_b32_e32 v2, 2, v23
	global_load_dword v23, v2, s[14:15]
	v_lshlrev_b32_e32 v2, 9, v26
	v_lshl_add_u64 v[24:25], v[24:25], 0, v[2:3]
	v_add_co_u32_e32 v26, vcc, s29, v24
	s_lshl_b32 s6, s6, 5
	s_nop 0
	v_addc_co_u32_e32 v27, vcc, 0, v25, vcc
	v_add_co_u32_e32 v28, vcc, s31, v24
	s_nop 1
	v_addc_co_u32_e32 v29, vcc, 0, v25, vcc
	v_add_co_u32_e32 v30, vcc, s34, v24
	s_nop 1
	v_addc_co_u32_e32 v31, vcc, 0, v25, vcc
	v_add_co_u32_e32 v32, vcc, s35, v24
	s_nop 1
	v_addc_co_u32_e32 v33, vcc, 0, v25, vcc
	global_load_dword v2, v[24:25], off
	global_load_dword v34, v[24:25], off offset:1024
	global_load_dword v35, v[24:25], off offset:2048
	global_load_dword v36, v[24:25], off offset:3072
	global_load_dword v37, v[26:27], off offset:1024
	global_load_dword v38, v[26:27], off offset:2048
	global_load_dword v39, v[26:27], off offset:3072
	global_load_dword v40, v[30:31], off offset:1024
	global_load_dword v41, v[28:29], off offset:-4096
	global_load_dword v42, v[28:29], off
	global_load_dword v43, v[28:29], off offset:1024
	global_load_dword v44, v[28:29], off offset:2048
	global_load_dword v45, v[28:29], off offset:3072
	global_load_dword v46, v[32:33], off offset:-4096
	global_load_dword v47, v[32:33], off
	v_add_co_u32_e32 v26, vcc, s36, v24
	s_waitcnt vmcnt(14)
	v_mul_f32_e32 v2, v23, v2
	v_addc_co_u32_e32 v27, vcc, 0, v25, vcc
	v_add_co_u32_e32 v28, vcc, s37, v24
	s_waitcnt vmcnt(10)
	v_mul_f32_e32 v37, v23, v37
	v_addc_co_u32_e32 v29, vcc, 0, v25, vcc
	v_add_co_u32_e32 v24, vcc, s38, v24
	global_load_dword v48, v[30:31], off offset:2048
	s_nop 0
	global_load_dword v30, v[30:31], off offset:3072
	s_nop 0
	global_load_dword v31, v[26:27], off offset:1024
	global_load_dword v49, v[26:27], off offset:2048
	s_nop 0
	global_load_dword v26, v[26:27], off offset:3072
	s_nop 0
	global_load_dword v27, v[32:33], off offset:1024
	global_load_dword v50, v[32:33], off offset:2048
	s_nop 0
	global_load_dword v32, v[32:33], off offset:3072
	s_nop 0
	global_load_dword v33, v[28:29], off offset:-4096
	global_load_dword v51, v[28:29], off
	global_load_dword v52, v[28:29], off offset:1024
	global_load_dword v53, v[28:29], off offset:2048
	s_nop 0
	global_load_dword v28, v[28:29], off offset:3072
	v_addc_co_u32_e32 v25, vcc, 0, v25, vcc
	global_load_dword v29, v[24:25], off
	global_load_dword v54, v[24:25], off offset:1024
	global_load_dword v55, v[24:25], off offset:2048
	s_nop 0
	global_load_dword v24, v[24:25], off offset:3072
	v_mul_f32_e32 v25, v23, v34
	v_mul_f32_e32 v34, v23, v35
	v_mul_f32_e32 v35, v23, v36
	s_waitcnt vmcnt(23)
	v_mul_f32_e32 v36, v23, v41
	v_mul_f32_e32 v38, v23, v38
	v_mul_f32_e32 v39, v23, v39
	s_waitcnt vmcnt(22)
	v_mul_f32_e32 v41, v23, v42
	s_waitcnt vmcnt(21)
	v_mul_f32_e32 v42, v23, v43
	s_waitcnt vmcnt(20)
	v_mul_f32_e32 v43, v23, v44
	s_waitcnt vmcnt(19)
	v_mul_f32_e32 v44, v23, v45
	s_waitcnt vmcnt(18)
	v_mul_f32_e32 v45, v23, v46
	v_mul_f32_e32 v40, v23, v40
	s_waitcnt vmcnt(17)
	v_mul_f32_e32 v47, v23, v47
	s_waitcnt vmcnt(16)
	v_mul_f32_e32 v46, v23, v48
	s_waitcnt vmcnt(15)
	v_mul_f32_e32 v30, v23, v30
	s_waitcnt vmcnt(14)
	v_mul_f32_e32 v31, v23, v31
	s_waitcnt vmcnt(13)
	v_mul_f32_e32 v49, v23, v49
	s_waitcnt vmcnt(12)
	v_mul_f32_e32 v26, v23, v26
	s_waitcnt vmcnt(11)
	v_mul_f32_e32 v27, v23, v27
	s_waitcnt vmcnt(10)
	v_mul_f32_e32 v48, v23, v50
	s_waitcnt vmcnt(9)
	v_mul_f32_e32 v32, v23, v32
	s_waitcnt vmcnt(8)
	v_mul_f32_e32 v33, v23, v33
	s_waitcnt vmcnt(7)
	v_mul_f32_e32 v50, v23, v51
	s_waitcnt vmcnt(6)
	v_mul_f32_e32 v51, v23, v52
	s_waitcnt vmcnt(5)
	v_mul_f32_e32 v52, v23, v53
	s_waitcnt vmcnt(4)
	v_mul_f32_e32 v28, v23, v28
	s_waitcnt vmcnt(3)
	v_mul_f32_e32 v29, v23, v29
	s_waitcnt vmcnt(2)
	v_mul_f32_e32 v53, v23, v54
	s_waitcnt vmcnt(1)
	v_mul_f32_e32 v54, v23, v55
	s_waitcnt vmcnt(0)
	v_mul_f32_e32 v23, v23, v24
	ds_write2_b32 v14, v2, v25 offset1:66
	ds_write2_b32 v14, v34, v35 offset0:132 offset1:198
	ds_write2_b32 v16, v36, v37 offset0:8 offset1:74
	ds_write2_b32 v16, v38, v39 offset0:140 offset1:206
	ds_write2_b32 v17, v41, v42 offset0:16 offset1:82
	ds_write2_b32 v17, v43, v44 offset0:148 offset1:214
	ds_write2_b32 v18, v45, v40 offset0:24 offset1:90
	ds_write2_b32 v18, v46, v30 offset0:156 offset1:222
	ds_write2_b32 v19, v47, v27 offset0:32 offset1:98
	ds_write2_b32 v19, v48, v32 offset0:164 offset1:230
	ds_write2_b32 v20, v33, v31 offset0:40 offset1:106
	ds_write2_b32 v20, v49, v26 offset0:172 offset1:238
	ds_write2_b32 v21, v50, v51 offset0:48 offset1:114
	ds_write2_b32 v21, v52, v28 offset0:180 offset1:246
	ds_write2_b32 v22, v29, v53 offset0:56 offset1:122
	ds_write2_b32 v22, v54, v23 offset0:188 offset1:254
	s_waitcnt lgkmcnt(0)
	ds_read2_b32 v[28:29], v10 offset0:33 offset1:41
	ds_read2_b32 v[30:31], v10 offset1:8
	ds_read2_b32 v[32:33], v10 offset0:66 offset1:74
	ds_read2_b32 v[34:35], v10 offset0:99 offset1:107
	ds_read2_b32 v[36:37], v10 offset0:132 offset1:140
	ds_read2_b32 v[38:39], v10 offset0:165 offset1:173
	ds_read2_b32 v[40:41], v10 offset0:198 offset1:206
	ds_read2_b32 v[42:43], v10 offset0:231 offset1:239
	v_lshlrev_b32_e32 v2, 4, v9
	v_lshl_add_u64 v[44:45], v[4:5], 0, s[6:7]
	v_lshl_add_u32 v2, s24, 8, v2
	v_lshl_add_u64 v[46:47], v[44:45], 0, v[2:3]
	s_waitcnt lgkmcnt(6)
	v_cvt_pk_bf16_f32 v24, v30, v28
	s_waitcnt lgkmcnt(4)
	v_cvt_pk_bf16_f32 v25, v32, v34
	s_waitcnt lgkmcnt(2)
	v_cvt_pk_bf16_f32 v26, v36, v38
	s_waitcnt lgkmcnt(0)
	v_cvt_pk_bf16_f32 v27, v40, v42
	global_store_dwordx4 v[46:47], v[24:27], off
	v_lshlrev_b32_e32 v2, 4, v11
	v_lshl_add_u32 v2, s24, 8, v2
	v_cvt_pk_bf16_f32 v24, v31, v29
	v_cvt_pk_bf16_f32 v25, v33, v35
	v_cvt_pk_bf16_f32 v26, v37, v39
	v_cvt_pk_bf16_f32 v27, v41, v43
	ds_read2_b32 v[30:31], v10 offset0:16 offset1:24
	ds_read2_b32 v[32:33], v10 offset0:49 offset1:57
	ds_read2_b32 v[34:35], v10 offset0:82 offset1:90
	ds_read2_b32 v[36:37], v10 offset0:115 offset1:123
	ds_read2_b32 v[38:39], v10 offset0:148 offset1:156
	ds_read2_b32 v[40:41], v10 offset0:181 offset1:189
	ds_read2_b32 v[42:43], v10 offset0:214 offset1:222
	ds_read2_b32 v[46:47], v10 offset0:247 offset1:255
	v_lshl_add_u64 v[28:29], v[44:45], 0, v[2:3]
	v_lshlrev_b32_e32 v2, 4, v12
	v_lshl_add_u32 v2, s24, 8, v2
	global_store_dwordx4 v[28:29], v[24:27], off
	v_lshl_add_u64 v[28:29], v[44:45], 0, v[2:3]
	v_lshlrev_b32_e32 v2, 4, v13
	v_lshl_add_u32 v2, s24, 8, v2
	s_waitcnt lgkmcnt(6)
	v_cvt_pk_bf16_f32 v24, v30, v32
	s_waitcnt lgkmcnt(4)
	v_cvt_pk_bf16_f32 v25, v34, v36
	s_waitcnt lgkmcnt(2)
	v_cvt_pk_bf16_f32 v26, v38, v40
	s_waitcnt lgkmcnt(0)
	v_cvt_pk_bf16_f32 v27, v42, v46
	global_store_dwordx4 v[28:29], v[24:27], off
	v_lshl_add_u64 v[28:29], v[44:45], 0, v[2:3]
	s_mov_b64 s[24:25], 0
	v_cvt_pk_bf16_f32 v24, v31, v33
	v_cvt_pk_bf16_f32 v25, v35, v37
	v_cvt_pk_bf16_f32 v26, v39, v41
	v_cvt_pk_bf16_f32 v27, v43, v47
	global_store_dwordx4 v[28:29], v[24:27], off
	s_waitcnt lgkmcnt(0)

.LBB0_310:
	v_readlane_b32 s0, v247, 5
	s_waitcnt lgkmcnt(0)
	v_lshrrev_b32_e32 v4, 5, v194
	v_mov_b32_e32 v155, 0
	v_lshlrev_b32_e32 v154, 4, v1
	v_readlane_b32 s1, v247, 6
	s_movk_i32 s6, 0x110
	v_lshlrev_b32_e32 v197, 3, v4
	v_lshl_add_u64 v[2:3], s[0:1], 0, v[154:155]
	v_lshlrev_b32_e32 v154, 12, v4
	v_lshl_add_u64 v[110:111], v[2:3], 0, v[154:155]
	v_lshlrev_b32_e32 v2, 4, v0
	v_and_b32_e32 v156, 0xf0, v2
	v_mov_b32_e32 v2, 0x880
	v_mad_u32_u24 v201, v195, s6, v2
	v_mov_b32_e32 v2, 0xcc0
	v_lshlrev_b32_e32 v154, 1, v1
	v_mad_u32_u24 v203, v195, s6, v2
	v_lshl_add_u64 v[2:3], s[76:77], 0, v[154:155]
	s_mov_b64 s[6:7], 0x4100200
	v_lshl_add_u64 v[120:121], v[2:3], 0, s[6:7]
	s_mov_b64 s[6:7], 0x8000
	v_lshl_add_u64 v[122:123], v[110:111], 0, s[6:7]
	s_mov_b64 s[6:7], 0xa000
	v_lshl_add_u64 v[124:125], v[110:111], 0, s[6:7]
	s_mov_b64 s[6:7], 0xc000
	v_lshl_add_u64 v[126:127], v[110:111], 0, s[6:7]
	s_mov_b64 s[6:7], 0xe000
	v_lshl_add_u64 v[128:129], v[110:111], 0, s[6:7]
	s_mov_b64 s[6:7], 0x4100100
	v_lshl_add_u64 v[130:131], v[2:3], 0, s[6:7]
	s_mov_b64 s[6:7], 0x2000
	v_lshl_add_u64 v[134:135], v[110:111], 0, s[6:7]
	s_mov_b64 s[6:7], 0x4000
	v_lshlrev_b32_e32 v212, 2, v4
	v_lshl_add_u64 v[136:137], v[110:111], 0, s[6:7]
	s_mov_b64 s[6:7], 0x6000
	v_and_b32_e32 v4, 32, v194
	v_mov_b32_e32 v5, v155
	v_lshl_add_u64 v[138:139], v[110:111], 0, s[6:7]
	v_lshl_add_u64 v[4:5], s[70:71], 0, v[4:5]
	s_mov_b64 s[6:7], 0x4180000
	v_lshl_add_u64 v[140:141], v[4:5], 0, s[6:7]
	s_mov_b64 s[6:7], 0x18000
	s_mov_b64 s[0:1], 0x10000
	v_lshl_add_u64 v[144:145], v[110:111], 0, s[6:7]
	s_mov_b64 s[6:7], 0x1a000
	v_lshl_add_u64 v[112:113], v[110:111], 0, s[0:1]
	s_mov_b64 s[0:1], 0x12000
	v_lshl_add_u64 v[146:147], v[110:111], 0, s[6:7]
	s_mov_b64 s[6:7], 0x1c000
	v_lshl_add_u64 v[114:115], v[110:111], 0, s[0:1]
	s_mov_b64 s[0:1], 0x14000
	v_lshl_add_u64 v[148:149], v[110:111], 0, s[6:7]
	s_mov_b64 s[6:7], 0x1e000
	v_readlane_b32 s8, v247, 31
	s_add_u32 s12, s76, 0x110000
	v_lshl_add_u64 v[116:117], v[110:111], 0, s[0:1]
	s_mov_b64 s[0:1], 0x16000
	v_mov_b32_e32 v157, v155
	v_lshl_add_u64 v[150:151], v[110:111], 0, s[6:7]
	s_mov_b64 s[6:7], 0x4100300
	v_readlane_b32 s9, v247, 32
	v_readlane_b32 s52, v247, 21
	v_readlane_b32 s90, v247, 19
	v_readlane_b32 s54, v247, 8
	v_readlane_b32 s66, v247, 10
	v_readlane_b32 s56, v247, 14
	v_readlane_b32 s58, v247, 17
	v_or_b32_e32 v196, 0xffffc000, v1
	s_addc_u32 s13, s77, 0
	v_lshl_add_u64 v[118:119], v[110:111], 0, s[0:1]
	v_mul_u32_u24_e32 v198, 0x110, v195
	v_or_b32_e32 v199, 4, v195
	v_or_b32_e32 v200, 8, v195
	v_or_b32_e32 v202, 12, v195
	v_cmp_eq_u32_e64 s[0:1], 3, v195
	v_cmp_ne_u32_e64 s[4:5], 3, v195
	v_or_b32_e32 v204, 16, v195
	v_or_b32_e32 v205, 20, v195
	v_or_b32_e32 v206, 24, v195
	v_or_b32_e32 v207, 28, v195
	v_or_b32_e32 v208, 32, v195
	v_or_b32_e32 v209, 36, v195
	v_or_b32_e32 v210, 40, v195
	v_or_b32_e32 v211, 44, v195
	v_mul_u32_u24_e32 v213, 0x110, v1
	v_lshl_add_u64 v[132:133], s[92:93], 0, v[156:157]
	v_lshl_add_u64 v[142:143], s[96:97], 0, v[154:155]
	s_andn2_b64 vcc, exec, s[8:9]
	v_lshl_add_u64 v[152:153], v[2:3], 0, s[6:7]
	v_readlane_b32 s53, v247, 22
	v_readlane_b32 s91, v247, 20
	v_readlane_b32 s55, v247, 9
	v_readlane_b32 s67, v247, 11
	v_readlane_b32 s57, v247, 15
	v_readlane_b32 s59, v247, 18
	s_cbranch_vccnz .LBB0_409
	v_readlane_b32 s8, v247, 7
	s_add_i32 s7, s8, -4
	s_lshr_b32 s7, s7, 1
	s_lshl_b32 s30, s63, 1
	s_bfe_u32 s31, s26, 0x10006
	s_lshr_b32 s6, s26, 7
	s_add_i32 s7, s7, 2
	s_and_b64 s[2:3], s[2:3], exec
	s_cselect_b32 s34, s7, s6
	s_lshl_b32 s2, s8, 14
	v_and_b32_e32 v166, 32, v0
	s_add_i32 s2, s2, 0
	v_lshrrev_b32_e32 v154, 1, v166
	v_add_u32_e32 v157, s2, v156
	v_add_u32_e32 v214, s2, v213
	v_lshl_add_u64 v[2:3], s[76:77], 0, v[154:155]
	s_mov_b64 s[2:3], 0x7300220
	v_lshl_add_u64 v[168:169], v[2:3], 0, s[2:3]
	s_lshl_b32 s2, s63, 6
	s_lshl_b32 s3, s31, 5
	s_or_b32 s2, s2, s3
	v_or_b32_e32 v215, s2, v1
	s_mov_b64 s[2:3], 0x7300120
	v_lshlrev_b32_e32 v158, 1, v197
	v_mov_b32_e32 v159, v155
	v_lshlrev_b32_e32 v162, 2, v197
	v_mov_b32_e32 v163, v155
	v_mov_b32_e32 v167, v155
	v_add_u32_e32 v4, 0xffffc000, v215
	v_lshlrev_b32_e32 v174, 7, v166
	v_lshl_or_b32 v174, v1, 4, v174
	v_mov_b32_e32 v175, v155
	v_lshl_add_u64 v[178:179], v[2:3], 0, s[2:3]
	s_mov_b64 s[2:3], 0x7300320
	s_mov_b32 s9, 0
	s_lshl_b32 s35, s33, 1
	v_lshl_add_u64 v[160:161], s[92:93], 0, v[158:159]
	v_lshl_add_u64 v[164:165], s[12:13], 0, v[162:163]
	s_lshl_b32 s36, s33, 6
	v_lshl_add_u64 v[170:171], s[76:77], 0, v[166:167]
	v_lshl_add_u64 v[172:173], s[70:71], 0, v[166:167]
	v_lshl_add_u64 v[176:177], s[76:77], 0, v[174:175]
	v_or_b32_e32 v180, 0x7300020, v154
	v_mov_b32_e32 v181, v155
	v_lshl_add_u64 v[182:183], v[2:3], 0, s[2:3]
	s_movk_i32 s37, 0x1a00
	s_movk_i32 s38, 0x7800
	s_mov_b64 s[14:15], 0x110640
	s_mov_b32 s39, 0x51c3000
	s_mov_b32 s40, 0x3d800000
	s_movk_i32 s41, 0x7f0
	s_mov_b64 s[16:17], 0x4180600
	s_mov_b64 s[18:19], 0x110440
	s_mov_b32 s42, 0x3e000000
	s_mov_b64 s[20:21], 0x4180400
	s_mov_b64 s[22:23], 0x110240
	s_mov_b32 s43, 0x3e800000
	s_mov_b64 s[24:25], 0x4180200
	s_mov_b64 s[26:27], 0x110040
	s_mov_b32 s44, 0x900000
	s_mov_b32 s45, 0x902000
	s_mov_b32 s46, 0x904000
	s_mov_b32 s47, 0x906000
	v_mov_b32_e32 v154, v4
	s_branch .LBB0_314

.LBB0_320:
	v_lshl_add_u64 v[96:97], v[184:185], 0, s[10:11]
	v_lshlrev_b32_e32 v92, 16, v86
	v_and_b32_e32 v93, 0xffff0000, v86
	v_lshlrev_b32_e32 v94, 16, v87
	v_and_b32_e32 v95, 0xffff0000, v87
	v_lshlrev_b32_e32 v86, 16, v88
	v_and_b32_e32 v87, 0xffff0000, v88
	v_add_co_u32_e32 v96, vcc, s39, v96
	v_lshlrev_b32_e32 v88, 16, v89
	v_and_b32_e32 v89, 0xffff0000, v89
	v_addc_co_u32_e32 v97, vcc, 0, v97, vcc
	v_add_f32_e32 v78, v78, v86
	v_add_f32_e32 v79, v79, v87
	global_store_dwordx4 v[96:97], v[92:95], off offset:1536
	global_store_dwordx4 v[96:97], v[86:89], off offset:1552
	s_lshl_b64 s[28:29], s[28:29], 5
	v_add_f32_e32 v84, v84, v94
	v_add_f32_e32 v80, v80, v88
	v_add_f32_e32 v85, v85, v95
	v_add_f32_e32 v81, v81, v89
	v_fma_f32 v86, v78, s40, -v86
	v_fma_f32 v87, v79, s40, -v87
	v_lshl_add_u64 v[96:97], v[144:145], 0, s[28:29]
	v_lshl_add_u64 v[100:101], v[146:147], 0, s[28:29]
	v_add_f32_e32 v104, v82, v92
	v_add_f32_e32 v105, v83, v93
	v_lshl_add_u64 v[82:83], v[148:149], 0, s[28:29]
	v_fma_f32 v84, v84, s40, -v94
	v_fma_f32 v85, v85, s40, -v95
	v_fma_f32 v88, v80, s40, -v88
	v_fma_f32 v81, v81, s40, -v89
	v_cvt_pk_bf16_f32 v80, v86, v87
	v_lshl_add_u64 v[86:87], v[150:151], 0, s[28:29]
	global_load_dwordx4 v[96:99], v[96:97], off
	v_cvt_pk_bf16_f32 v79, v84, v85
	global_load_dwordx4 v[100:103], v[100:101], off
	v_cvt_pk_bf16_f32 v81, v88, v81
	global_load_dwordx4 v[82:85], v[82:83], off
	v_fma_f32 v92, v104, s40, -v92
	global_load_dwordx4 v[86:89], v[86:87], off
	v_fma_f32 v93, v105, s40, -v93
	v_cvt_pk_bf16_f32 v78, v92, v93
	s_add_i32 s49, s49, 1
	s_add_u32 s10, s10, 64
	s_addc_u32 s11, s11, 0
	s_add_u32 s6, s6, 16
	s_addc_u32 s7, s7, 0
	s_cmpk_lg_i32 s10, 0x200
	v_lshl_add_u64 v[90:91], v[90:91], 0, 32
	s_waitcnt vmcnt(3)
	v_mfma_f32_32x32x16_bf16 v[2:17], v[78:81], v[96:99], v[2:17]
	s_waitcnt vmcnt(2)
	v_mfma_f32_32x32x16_bf16 v[18:33], v[78:81], v[100:103], v[18:33]
	s_waitcnt vmcnt(1)
	v_mfma_f32_32x32x16_bf16 v[34:49], v[78:81], v[82:85], v[34:49]
	s_waitcnt vmcnt(0)
	v_mfma_f32_32x32x16_bf16 v[50:65], v[78:81], v[86:89], v[50:65]
	s_cbranch_scc0 .LBB0_322
	v_mov_b64_e32 v[80:81], v[76:77]
	v_mov_b64_e32 v[84:85], v[72:73]
	v_mov_b64_e32 v[88:89], v[68:69]
	v_mov_b64_e32 v[78:79], v[74:75]
	v_mov_b64_e32 v[82:83], v[70:71]
	v_mov_b64_e32 v[86:87], v[66:67]
	s_cmpk_eq_i32 s10, 0x1c0
	s_mov_b64 s[28:29], s[6:7]
	s_cbranch_scc0 .LBB0_319
	s_branch .LBB0_320

.LBB0_333:
	v_lshl_add_u64 v[90:91], s[10:11], 4, v[176:177]
	v_add_co_u32_e32 v82, vcc, 0x918000, v90
	s_mov_b32 s8, s49
	s_nop 0
	v_addc_co_u32_e32 v83, vcc, 0, v91, vcc
	v_add_co_u32_e32 v86, vcc, 0x91a000, v90
	s_nop 1
	v_addc_co_u32_e32 v87, vcc, 0, v91, vcc
	v_add_co_u32_e32 v92, vcc, 0x91c000, v90
	global_load_dwordx4 v[82:85], v[82:83], off offset:512
	s_nop 0
	global_load_dwordx4 v[86:89], v[86:87], off offset:512
	v_addc_co_u32_e32 v93, vcc, 0, v91, vcc
	v_add_co_u32_e32 v94, vcc, 0x91e000, v90
	s_nop 1
	v_addc_co_u32_e32 v95, vcc, 0, v91, vcc
	global_load_dwordx4 v[90:93], v[92:93], off offset:512
	s_nop 0
	global_load_dwordx4 v[94:97], v[94:95], off offset:512

.LBB0_343:
	v_lshl_add_u64 v[96:97], v[184:185], 0, s[10:11]
	v_lshlrev_b32_e32 v92, 16, v86
	v_and_b32_e32 v93, 0xffff0000, v86
	v_lshlrev_b32_e32 v94, 16, v87
	v_and_b32_e32 v95, 0xffff0000, v87
	v_lshlrev_b32_e32 v86, 16, v88
	v_and_b32_e32 v87, 0xffff0000, v88
	v_add_co_u32_e32 v96, vcc, s39, v96
	v_lshlrev_b32_e32 v88, 16, v89
	v_and_b32_e32 v89, 0xffff0000, v89
	v_addc_co_u32_e32 v97, vcc, 0, v97, vcc
	v_add_f32_e32 v78, v78, v86
	v_add_f32_e32 v79, v79, v87
	global_store_dwordx4 v[96:97], v[92:95], off offset:1024
	global_store_dwordx4 v[96:97], v[86:89], off offset:1040
	s_lshl_b64 s[28:29], s[28:29], 5
	v_add_f32_e32 v84, v84, v94
	v_add_f32_e32 v80, v80, v88
	v_add_f32_e32 v85, v85, v95
	v_add_f32_e32 v81, v81, v89
	v_fma_f32 v86, v78, s42, -v86
	v_fma_f32 v87, v79, s42, -v87
	v_lshl_add_u64 v[96:97], v[112:113], 0, s[28:29]
	v_lshl_add_u64 v[100:101], v[114:115], 0, s[28:29]
	v_add_f32_e32 v104, v82, v92
	v_add_f32_e32 v105, v83, v93
	v_lshl_add_u64 v[82:83], v[116:117], 0, s[28:29]
	v_fma_f32 v84, v84, s42, -v94
	v_fma_f32 v85, v85, s42, -v95
	v_fma_f32 v88, v80, s42, -v88
	v_fma_f32 v81, v81, s42, -v89
	v_cvt_pk_bf16_f32 v80, v86, v87
	v_lshl_add_u64 v[86:87], v[118:119], 0, s[28:29]
	global_load_dwordx4 v[96:99], v[96:97], off
	v_cvt_pk_bf16_f32 v79, v84, v85
	global_load_dwordx4 v[100:103], v[100:101], off
	v_cvt_pk_bf16_f32 v81, v88, v81
	global_load_dwordx4 v[82:85], v[82:83], off
	v_fma_f32 v92, v104, s42, -v92
	global_load_dwordx4 v[86:89], v[86:87], off
	v_fma_f32 v93, v105, s42, -v93
	v_cvt_pk_bf16_f32 v78, v92, v93
	s_add_i32 s49, s49, 1
	s_add_u32 s10, s10, 64
	s_addc_u32 s11, s11, 0
	s_add_u32 s6, s6, 16
	s_addc_u32 s7, s7, 0
	s_cmpk_lg_i32 s10, 0x200
	v_lshl_add_u64 v[90:91], v[90:91], 0, 32
	s_waitcnt vmcnt(3)
	v_mfma_f32_32x32x16_bf16 v[2:17], v[78:81], v[96:99], v[2:17]
	s_waitcnt vmcnt(2)
	v_mfma_f32_32x32x16_bf16 v[18:33], v[78:81], v[100:103], v[18:33]
	s_waitcnt vmcnt(1)
	v_mfma_f32_32x32x16_bf16 v[34:49], v[78:81], v[82:85], v[34:49]
	s_waitcnt vmcnt(0)
	v_mfma_f32_32x32x16_bf16 v[50:65], v[78:81], v[86:89], v[50:65]
	s_cbranch_scc0 .LBB0_345
	v_mov_b64_e32 v[80:81], v[76:77]
	v_mov_b64_e32 v[84:85], v[72:73]
	v_mov_b64_e32 v[88:89], v[68:69]
	v_mov_b64_e32 v[78:79], v[74:75]
	v_mov_b64_e32 v[82:83], v[70:71]
	v_mov_b64_e32 v[86:87], v[66:67]
	s_cmpk_eq_i32 s10, 0x1c0
	s_mov_b64 s[28:29], s[6:7]
	s_cbranch_scc0 .LBB0_342
	s_branch .LBB0_343

.LBB0_356:
	v_lshl_add_u64 v[90:91], s[10:11], 4, v[176:177]
	v_add_co_u32_e32 v82, vcc, 0x910000, v90
	s_mov_b32 s8, s49
	s_nop 0
	v_addc_co_u32_e32 v83, vcc, 0, v91, vcc
	v_add_co_u32_e32 v86, vcc, 0x912000, v90
	s_nop 1
	v_addc_co_u32_e32 v87, vcc, 0, v91, vcc
	v_add_co_u32_e32 v92, vcc, 0x914000, v90
	global_load_dwordx4 v[82:85], v[82:83], off offset:512
	s_nop 0
	global_load_dwordx4 v[86:89], v[86:87], off offset:512
	v_addc_co_u32_e32 v93, vcc, 0, v91, vcc
	v_add_co_u32_e32 v94, vcc, 0x916000, v90
	s_nop 1
	v_addc_co_u32_e32 v95, vcc, 0, v91, vcc
	global_load_dwordx4 v[90:93], v[92:93], off offset:512
	s_nop 0
	global_load_dwordx4 v[94:97], v[94:95], off offset:512

.LBB0_367:
	v_lshl_add_u64 v[96:97], v[184:185], 0, s[10:11]
	v_lshlrev_b32_e32 v92, 16, v86
	v_and_b32_e32 v93, 0xffff0000, v86
	v_lshlrev_b32_e32 v94, 16, v87
	v_and_b32_e32 v95, 0xffff0000, v87
	v_lshlrev_b32_e32 v86, 16, v88
	v_and_b32_e32 v87, 0xffff0000, v88
	v_add_co_u32_e32 v96, vcc, s39, v96
	v_lshlrev_b32_e32 v88, 16, v89
	v_and_b32_e32 v89, 0xffff0000, v89
	v_addc_co_u32_e32 v97, vcc, 0, v97, vcc
	v_add_f32_e32 v78, v78, v86
	v_add_f32_e32 v79, v79, v87
	global_store_dwordx4 v[96:97], v[92:95], off offset:512
	global_store_dwordx4 v[96:97], v[86:89], off offset:528
	s_lshl_b64 s[28:29], s[28:29], 5
	v_add_f32_e32 v84, v84, v94
	v_add_f32_e32 v80, v80, v88
	v_add_f32_e32 v85, v85, v95
	v_add_f32_e32 v81, v81, v89
	v_fma_f32 v86, v78, s43, -v86
	v_fma_f32 v87, v79, s43, -v87
	v_lshl_add_u64 v[96:97], v[122:123], 0, s[28:29]
	v_lshl_add_u64 v[100:101], v[124:125], 0, s[28:29]
	v_add_f32_e32 v104, v82, v92
	v_add_f32_e32 v105, v83, v93
	v_lshl_add_u64 v[82:83], v[126:127], 0, s[28:29]
	v_fma_f32 v84, v84, s43, -v94
	v_fma_f32 v85, v85, s43, -v95
	v_fma_f32 v88, v80, s43, -v88
	v_fma_f32 v81, v81, s43, -v89
	v_cvt_pk_bf16_f32 v80, v86, v87
	v_lshl_add_u64 v[86:87], v[128:129], 0, s[28:29]
	global_load_dwordx4 v[96:99], v[96:97], off
	v_cvt_pk_bf16_f32 v79, v84, v85
	global_load_dwordx4 v[100:103], v[100:101], off
	v_cvt_pk_bf16_f32 v81, v88, v81
	global_load_dwordx4 v[82:85], v[82:83], off
	v_fma_f32 v92, v104, s43, -v92
	global_load_dwordx4 v[86:89], v[86:87], off
	v_fma_f32 v93, v105, s43, -v93
	v_cvt_pk_bf16_f32 v78, v92, v93
	s_add_i32 s49, s49, 1
	s_add_u32 s10, s10, 64
	s_addc_u32 s11, s11, 0
	s_add_u32 s6, s6, 16
	s_addc_u32 s7, s7, 0
	s_cmpk_lg_i32 s10, 0x200
	v_lshl_add_u64 v[90:91], v[90:91], 0, 32
	s_waitcnt vmcnt(3)
	v_mfma_f32_32x32x16_bf16 v[2:17], v[78:81], v[96:99], v[2:17]
	s_waitcnt vmcnt(2)
	v_mfma_f32_32x32x16_bf16 v[18:33], v[78:81], v[100:103], v[18:33]
	s_waitcnt vmcnt(1)
	v_mfma_f32_32x32x16_bf16 v[34:49], v[78:81], v[82:85], v[34:49]
	s_waitcnt vmcnt(0)
	v_mfma_f32_32x32x16_bf16 v[50:65], v[78:81], v[86:89], v[50:65]
	s_cbranch_scc0 .LBB0_369
	v_mov_b64_e32 v[80:81], v[76:77]
	v_mov_b64_e32 v[84:85], v[72:73]
	v_mov_b64_e32 v[88:89], v[68:69]
	v_mov_b64_e32 v[78:79], v[74:75]
	v_mov_b64_e32 v[82:83], v[70:71]
	v_mov_b64_e32 v[86:87], v[66:67]
	s_cmpk_eq_i32 s10, 0x1c0
	s_mov_b64 s[28:29], s[6:7]
	s_cbranch_scc0 .LBB0_366
	s_branch .LBB0_367

.LBB0_380:
	v_lshl_add_u64 v[90:91], s[10:11], 4, v[176:177]
	v_add_co_u32_e32 v82, vcc, 0x908000, v90
	s_mov_b32 s8, s49
	s_nop 0
	v_addc_co_u32_e32 v83, vcc, 0, v91, vcc
	v_add_co_u32_e32 v86, vcc, 0x90a000, v90
	s_nop 1
	v_addc_co_u32_e32 v87, vcc, 0, v91, vcc
	v_add_co_u32_e32 v92, vcc, 0x90c000, v90
	global_load_dwordx4 v[82:85], v[82:83], off offset:512
	s_nop 0
	global_load_dwordx4 v[86:89], v[86:87], off offset:512
	v_addc_co_u32_e32 v93, vcc, 0, v91, vcc
	v_add_co_u32_e32 v94, vcc, 0x90e000, v90
	s_nop 1
	v_addc_co_u32_e32 v95, vcc, 0, v91, vcc
	global_load_dwordx4 v[90:93], v[92:93], off offset:512
	s_nop 0
	global_load_dwordx4 v[94:97], v[94:95], off offset:512

.LBB0_391:
	v_lshl_add_u64 v[100:101], v[184:185], 0, s[2:3]
	v_add_co_u32_e32 v100, vcc, s39, v100
	v_lshlrev_b32_e32 v96, 16, v86
	v_and_b32_e32 v97, 0xffff0000, v86
	v_lshlrev_b32_e32 v98, 16, v87
	v_and_b32_e32 v99, 0xffff0000, v87
	v_addc_co_u32_e32 v101, vcc, 0, v101, vcc
	v_lshl_add_u64 v[108:109], s[76:77], 0, v[94:95]
	v_lshlrev_b32_e32 v86, 16, v88
	v_and_b32_e32 v87, 0xffff0000, v88
	v_lshlrev_b32_e32 v88, 16, v89
	v_and_b32_e32 v89, 0xffff0000, v89
	global_store_dwordx4 v[100:101], v[96:99], off
	global_store_dwordx4 v[100:101], v[86:89], off offset:16
	v_add_co_u32_e32 v100, vcc, s44, v108
	v_add_f32_e32 v159, v82, v96
	s_nop 0
	v_addc_co_u32_e32 v101, vcc, 0, v109, vcc
	v_add_co_u32_e32 v104, vcc, s45, v108
	v_add_f32_e32 v78, v78, v86
	s_nop 0
	v_addc_co_u32_e32 v105, vcc, 0, v109, vcc
	v_add_co_u32_e32 v82, vcc, s46, v108
	v_add_f32_e32 v163, v83, v97
	v_add_f32_e32 v79, v79, v87
	v_add_f32_e32 v80, v80, v88
	v_addc_co_u32_e32 v83, vcc, 0, v109, vcc
	v_fma_f32 v86, v78, 0.5, -v86
	v_add_f32_e32 v84, v84, v98
	v_add_f32_e32 v85, v85, v99
	v_add_f32_e32 v81, v81, v89
	v_fma_f32 v87, v79, 0.5, -v87
	v_fma_f32 v88, v80, 0.5, -v88
	v_cvt_pk_bf16_f32 v80, v86, v87
	v_add_co_u32_e32 v86, vcc, s47, v108
	v_fma_f32 v84, v84, 0.5, -v98
	v_fma_f32 v85, v85, 0.5, -v99
	v_fma_f32 v81, v81, 0.5, -v89
	v_addc_co_u32_e32 v87, vcc, 0, v109, vcc
	global_load_dwordx4 v[100:103], v[100:101], off
	v_cvt_pk_bf16_f32 v79, v84, v85
	global_load_dwordx4 v[104:107], v[104:105], off
	v_cvt_pk_bf16_f32 v81, v88, v81
	global_load_dwordx4 v[82:85], v[82:83], off
	v_fma_f32 v96, v159, 0.5, -v96
	global_load_dwordx4 v[86:89], v[86:87], off
	v_fma_f32 v97, v163, 0.5, -v97
	v_cvt_pk_bf16_f32 v78, v96, v97
	s_add_u32 s2, s2, 64
	s_addc_u32 s3, s3, 0
	v_add_u32_e32 v94, 0x200, v94
	v_lshl_add_u64 v[90:91], v[90:91], 0, 64
	s_cmpk_lg_i32 s2, 0x200
	v_lshl_add_u64 v[92:93], v[92:93], 0, 32
	s_waitcnt vmcnt(3)
	v_mfma_f32_32x32x16_bf16 v[2:17], v[78:81], v[100:103], v[2:17]
	s_waitcnt vmcnt(2)
	v_mfma_f32_32x32x16_bf16 v[18:33], v[78:81], v[104:107], v[18:33]
	s_waitcnt vmcnt(1)
	v_mfma_f32_32x32x16_bf16 v[34:49], v[78:81], v[82:85], v[34:49]
	s_waitcnt vmcnt(0)
	v_mfma_f32_32x32x16_bf16 v[50:65], v[78:81], v[86:89], v[50:65]
	s_cbranch_scc0 .LBB0_393
	v_mov_b64_e32 v[80:81], v[76:77]
	v_mov_b64_e32 v[84:85], v[72:73]
	v_mov_b64_e32 v[88:89], v[68:69]
	v_mov_b64_e32 v[78:79], v[74:75]
	v_mov_b64_e32 v[82:83], v[70:71]
	v_mov_b64_e32 v[86:87], v[66:67]
	s_cmpk_eq_i32 s2, 0x1c0
	s_cbranch_scc0 .LBB0_390
	s_branch .LBB0_391

.LBB0_404:
	v_lshl_add_u64 v[90:91], s[2:3], 4, v[176:177]
	v_add_co_u32_e32 v82, vcc, 0x900000, v90
	s_mov_b32 s8, s28
	s_nop 0
	v_addc_co_u32_e32 v83, vcc, 0, v91, vcc
	v_add_co_u32_e32 v86, vcc, 0x902000, v90
	s_nop 1
	v_addc_co_u32_e32 v87, vcc, 0, v91, vcc
	v_add_co_u32_e32 v92, vcc, 0x904000, v90
	global_load_dwordx4 v[82:85], v[82:83], off offset:512
	s_nop 0
	global_load_dwordx4 v[86:89], v[86:87], off offset:512
	v_addc_co_u32_e32 v93, vcc, 0, v91, vcc
	v_add_co_u32_e32 v94, vcc, 0x906000, v90
	s_nop 1
	v_addc_co_u32_e32 v95, vcc, 0, v91, vcc
	global_load_dwordx4 v[90:93], v[92:93], off offset:512
	s_nop 0
	global_load_dwordx4 v[94:97], v[94:95], off offset:512

.LBB0_409:
	v_readlane_b32 s2, v247, 7
	s_cmp_lg_u32 s2, 4
	s_cselect_b64 s[2:3], -1, 0
	s_cmp_gt_i32 s63, 15
	s_cselect_b64 s[6:7], -1, 0
	s_or_b64 s[2:3], s[2:3], s[6:7]
	s_and_b64 vcc, exec, s[2:3]
	s_cbranch_vccnz .LBB0_507
	s_add_i32 s2, 0, 0x10000
	v_and_b32_e32 v164, 32, v0
	v_add_u32_e32 v184, s2, v156
	v_mov_b32_e32 v157, 0
	v_lshrrev_b32_e32 v156, 1, v164
	v_add_u32_e32 v185, s2, v213
	v_lshl_add_u64 v[2:3], s[76:77], 0, v[156:157]
	s_mov_b64 s[2:3], 0x7300320
	v_lshl_add_u64 v[166:167], v[2:3], 0, s[2:3]
	s_mov_b64 s[2:3], 0x7300220
	v_lshlrev_b32_e32 v154, 1, v197
	v_mov_b32_e32 v155, v157
	v_lshlrev_b32_e32 v160, 2, v197
	v_mov_b32_e32 v161, v157
	v_mov_b32_e32 v165, v157
	v_lshlrev_b32_e32 v172, 7, v164
	v_lshl_or_b32 v172, v1, 4, v172
	v_mov_b32_e32 v173, v157
	v_lshl_add_u64 v[176:177], v[2:3], 0, s[2:3]
	s_mov_b64 s[2:3], 0x7300120
	s_mov_b32 s9, 0
	v_lshl_add_u64 v[158:159], s[92:93], 0, v[154:155]
	v_lshl_add_u64 v[162:163], s[12:13], 0, v[160:161]
	v_lshl_add_u64 v[168:169], s[76:77], 0, v[164:165]
	v_lshl_add_u64 v[170:171], s[70:71], 0, v[164:165]
	v_lshl_add_u64 v[174:175], s[76:77], 0, v[172:173]
	v_lshl_add_u64 v[178:179], v[2:3], 0, s[2:3]
	v_or_b32_e32 v180, 0x7300020, v156
	v_mov_b32_e32 v181, v157
	s_movk_i32 s30, 0x1a00
	s_movk_i32 s31, 0x7800
	s_mov_b64 s[14:15], 0x110640
	s_mov_b32 s34, 0x51c3000
	s_mov_b32 s35, 0x3d800000
	s_movk_i32 s36, 0x7f0
	s_mov_b64 s[16:17], 0x4180600
	s_mov_b64 s[18:19], 0x110440
	s_mov_b32 s37, 0x3e000000
	s_mov_b64 s[20:21], 0x4180400
	s_mov_b64 s[22:23], 0x110040
	s_mov_b32 s38, 0x900000
	s_mov_b32 s39, 0x902000
	s_mov_b32 s40, 0x904000
	s_mov_b32 s41, 0x906000
	s_mov_b64 s[24:25], 0x110240
	s_mov_b32 s42, 0x3e800000
	s_mov_b64 s[26:27], 0x4180200
	s_mov_b32 s43, s63
	s_branch .LBB0_413

.LBB0_418:
	v_lshl_add_u64 v[100:101], v[90:91], 0, s[10:11]
	v_lshlrev_b32_e32 v96, 16, v86
	v_and_b32_e32 v97, 0xffff0000, v86
	v_lshlrev_b32_e32 v98, 16, v87
	v_and_b32_e32 v99, 0xffff0000, v87
	v_lshlrev_b32_e32 v86, 16, v88
	v_and_b32_e32 v87, 0xffff0000, v88
	v_add_co_u32_e32 v100, vcc, s34, v100
	v_lshlrev_b32_e32 v88, 16, v89
	v_and_b32_e32 v89, 0xffff0000, v89
	v_addc_co_u32_e32 v101, vcc, 0, v101, vcc
	v_add_f32_e32 v78, v78, v86
	v_add_f32_e32 v79, v79, v87
	global_store_dwordx4 v[100:101], v[96:99], off offset:1536
	global_store_dwordx4 v[100:101], v[86:89], off offset:1552
	s_lshl_b64 s[28:29], s[28:29], 5
	v_add_f32_e32 v84, v84, v98
	v_add_f32_e32 v80, v80, v88
	v_add_f32_e32 v85, v85, v99
	v_add_f32_e32 v81, v81, v89
	v_fma_f32 v86, v78, s35, -v86
	v_fma_f32 v87, v79, s35, -v87
	v_lshl_add_u64 v[100:101], v[144:145], 0, s[28:29]
	v_lshl_add_u64 v[104:105], v[146:147], 0, s[28:29]
	v_add_f32_e32 v108, v82, v96
	v_add_f32_e32 v109, v83, v97
	v_lshl_add_u64 v[82:83], v[148:149], 0, s[28:29]
	v_fma_f32 v84, v84, s35, -v98
	v_fma_f32 v85, v85, s35, -v99
	v_fma_f32 v88, v80, s35, -v88
	v_fma_f32 v81, v81, s35, -v89
	v_cvt_pk_bf16_f32 v80, v86, v87
	v_lshl_add_u64 v[86:87], v[150:151], 0, s[28:29]
	global_load_dwordx4 v[100:103], v[100:101], off
	v_cvt_pk_bf16_f32 v79, v84, v85
	global_load_dwordx4 v[104:107], v[104:105], off
	v_cvt_pk_bf16_f32 v81, v88, v81
	global_load_dwordx4 v[82:85], v[82:83], off
	v_fma_f32 v96, v108, s35, -v96
	global_load_dwordx4 v[86:89], v[86:87], off
	v_fma_f32 v97, v109, s35, -v97
	v_cvt_pk_bf16_f32 v78, v96, v97
	s_add_i32 s47, s47, 1
	s_add_u32 s10, s10, 64
	s_addc_u32 s11, s11, 0
	s_add_u32 s6, s6, 16
	s_addc_u32 s7, s7, 0
	s_cmpk_lg_i32 s10, 0x200
	v_lshl_add_u64 v[92:93], v[92:93], 0, 32
	s_waitcnt vmcnt(3)
	v_mfma_f32_32x32x16_bf16 v[2:17], v[78:81], v[100:103], v[2:17]
	s_waitcnt vmcnt(2)
	v_mfma_f32_32x32x16_bf16 v[18:33], v[78:81], v[104:107], v[18:33]
	s_waitcnt vmcnt(1)
	v_mfma_f32_32x32x16_bf16 v[34:49], v[78:81], v[82:85], v[34:49]
	s_waitcnt vmcnt(0)
	v_mfma_f32_32x32x16_bf16 v[50:65], v[78:81], v[86:89], v[50:65]
	s_cbranch_scc0 .LBB0_420
	v_mov_b64_e32 v[80:81], v[76:77]
	v_mov_b64_e32 v[84:85], v[72:73]
	v_mov_b64_e32 v[88:89], v[68:69]
	v_mov_b64_e32 v[78:79], v[74:75]
	v_mov_b64_e32 v[82:83], v[70:71]
	v_mov_b64_e32 v[86:87], v[66:67]
	s_cmpk_eq_i32 s10, 0x1c0
	s_mov_b64 s[28:29], s[6:7]
	s_cbranch_scc0 .LBB0_417
	s_branch .LBB0_418

.LBB0_431:
	v_lshl_add_u64 v[90:91], s[10:11], 4, v[174:175]
	v_add_co_u32_e32 v82, vcc, 0x918000, v90
	s_mov_b32 s8, s47
	s_nop 0
	v_addc_co_u32_e32 v83, vcc, 0, v91, vcc
	v_add_co_u32_e32 v86, vcc, 0x91a000, v90
	s_nop 1
	v_addc_co_u32_e32 v87, vcc, 0, v91, vcc
	v_add_co_u32_e32 v92, vcc, 0x91c000, v90
	global_load_dwordx4 v[82:85], v[82:83], off offset:512
	s_nop 0
	global_load_dwordx4 v[86:89], v[86:87], off offset:512
	v_addc_co_u32_e32 v93, vcc, 0, v91, vcc
	v_add_co_u32_e32 v94, vcc, 0x91e000, v90
	s_nop 1
	v_addc_co_u32_e32 v95, vcc, 0, v91, vcc
	global_load_dwordx4 v[90:93], v[92:93], off offset:512
	s_nop 0
	global_load_dwordx4 v[94:97], v[94:95], off offset:512

.LBB0_441:
	v_lshl_add_u64 v[100:101], v[90:91], 0, s[10:11]
	v_lshlrev_b32_e32 v96, 16, v86
	v_and_b32_e32 v97, 0xffff0000, v86
	v_lshlrev_b32_e32 v98, 16, v87
	v_and_b32_e32 v99, 0xffff0000, v87
	v_lshlrev_b32_e32 v86, 16, v88
	v_and_b32_e32 v87, 0xffff0000, v88
	v_add_co_u32_e32 v100, vcc, s34, v100
	v_lshlrev_b32_e32 v88, 16, v89
	v_and_b32_e32 v89, 0xffff0000, v89
	v_addc_co_u32_e32 v101, vcc, 0, v101, vcc
	v_add_f32_e32 v78, v78, v86
	v_add_f32_e32 v79, v79, v87
	global_store_dwordx4 v[100:101], v[96:99], off offset:1024
	global_store_dwordx4 v[100:101], v[86:89], off offset:1040
	s_lshl_b64 s[28:29], s[28:29], 5
	v_add_f32_e32 v84, v84, v98
	v_add_f32_e32 v80, v80, v88
	v_add_f32_e32 v85, v85, v99
	v_add_f32_e32 v81, v81, v89
	v_fma_f32 v86, v78, s37, -v86
	v_fma_f32 v87, v79, s37, -v87
	v_lshl_add_u64 v[100:101], v[112:113], 0, s[28:29]
	v_lshl_add_u64 v[104:105], v[114:115], 0, s[28:29]
	v_add_f32_e32 v108, v82, v96
	v_add_f32_e32 v109, v83, v97
	v_lshl_add_u64 v[82:83], v[116:117], 0, s[28:29]
	v_fma_f32 v84, v84, s37, -v98
	v_fma_f32 v85, v85, s37, -v99
	v_fma_f32 v88, v80, s37, -v88
	v_fma_f32 v81, v81, s37, -v89
	v_cvt_pk_bf16_f32 v80, v86, v87
	v_lshl_add_u64 v[86:87], v[118:119], 0, s[28:29]
	global_load_dwordx4 v[100:103], v[100:101], off
	v_cvt_pk_bf16_f32 v79, v84, v85
	global_load_dwordx4 v[104:107], v[104:105], off
	v_cvt_pk_bf16_f32 v81, v88, v81
	global_load_dwordx4 v[82:85], v[82:83], off
	v_fma_f32 v96, v108, s37, -v96
	global_load_dwordx4 v[86:89], v[86:87], off
	v_fma_f32 v97, v109, s37, -v97
	v_cvt_pk_bf16_f32 v78, v96, v97
	s_add_i32 s47, s47, 1
	s_add_u32 s10, s10, 64
	s_addc_u32 s11, s11, 0
	s_add_u32 s6, s6, 16
	s_addc_u32 s7, s7, 0
	s_cmpk_lg_i32 s10, 0x200
	v_lshl_add_u64 v[92:93], v[92:93], 0, 32
	s_waitcnt vmcnt(3)
	v_mfma_f32_32x32x16_bf16 v[2:17], v[78:81], v[100:103], v[2:17]
	s_waitcnt vmcnt(2)
	v_mfma_f32_32x32x16_bf16 v[18:33], v[78:81], v[104:107], v[18:33]
	s_waitcnt vmcnt(1)
	v_mfma_f32_32x32x16_bf16 v[34:49], v[78:81], v[82:85], v[34:49]
	s_waitcnt vmcnt(0)
	v_mfma_f32_32x32x16_bf16 v[50:65], v[78:81], v[86:89], v[50:65]
	s_cbranch_scc0 .LBB0_443
	v_mov_b64_e32 v[80:81], v[76:77]
	v_mov_b64_e32 v[84:85], v[72:73]
	v_mov_b64_e32 v[88:89], v[68:69]
	v_mov_b64_e32 v[78:79], v[74:75]
	v_mov_b64_e32 v[82:83], v[70:71]
	v_mov_b64_e32 v[86:87], v[66:67]
	s_cmpk_eq_i32 s10, 0x1c0
	s_mov_b64 s[28:29], s[6:7]
	s_cbranch_scc0 .LBB0_440
	s_branch .LBB0_441

.LBB0_454:
	v_lshl_add_u64 v[90:91], s[10:11], 4, v[174:175]
	v_add_co_u32_e32 v82, vcc, 0x910000, v90
	s_mov_b32 s8, s47
	s_nop 0
	v_addc_co_u32_e32 v83, vcc, 0, v91, vcc
	v_add_co_u32_e32 v86, vcc, 0x912000, v90
	s_nop 1
	v_addc_co_u32_e32 v87, vcc, 0, v91, vcc
	v_add_co_u32_e32 v92, vcc, 0x914000, v90
	global_load_dwordx4 v[82:85], v[82:83], off offset:512
	s_nop 0
	global_load_dwordx4 v[86:89], v[86:87], off offset:512
	v_addc_co_u32_e32 v93, vcc, 0, v91, vcc
	v_add_co_u32_e32 v94, vcc, 0x916000, v90
	s_nop 1
	v_addc_co_u32_e32 v95, vcc, 0, v91, vcc
	global_load_dwordx4 v[90:93], v[92:93], off offset:512
	s_nop 0
	global_load_dwordx4 v[94:97], v[94:95], off offset:512

.LBB0_466:
	v_lshl_add_u64 v[102:103], v[94:95], 0, s[6:7]
	v_add_co_u32_e32 v102, vcc, s34, v102
	v_lshlrev_b32_e32 v98, 16, v86
	v_and_b32_e32 v99, 0xffff0000, v86
	v_lshlrev_b32_e32 v100, 16, v87
	v_and_b32_e32 v101, 0xffff0000, v87
	v_addc_co_u32_e32 v103, vcc, 0, v103, vcc
	v_lshl_add_u64 v[182:183], s[76:77], 0, v[96:97]
	v_lshlrev_b32_e32 v86, 16, v88
	v_and_b32_e32 v87, 0xffff0000, v88
	v_lshlrev_b32_e32 v88, 16, v89
	v_and_b32_e32 v89, 0xffff0000, v89
	global_store_dwordx4 v[102:103], v[98:101], off
	global_store_dwordx4 v[102:103], v[86:89], off offset:16
	v_add_co_u32_e32 v102, vcc, s38, v182
	v_add_f32_e32 v155, v82, v98
	s_nop 0
	v_addc_co_u32_e32 v103, vcc, 0, v183, vcc
	v_add_co_u32_e32 v106, vcc, s39, v182
	v_add_f32_e32 v78, v78, v86
	s_nop 0
	v_addc_co_u32_e32 v107, vcc, 0, v183, vcc
	v_add_co_u32_e32 v82, vcc, s40, v182
	v_add_f32_e32 v156, v83, v99
	v_add_f32_e32 v79, v79, v87
	v_add_f32_e32 v80, v80, v88
	v_addc_co_u32_e32 v83, vcc, 0, v183, vcc
	v_fma_f32 v86, v78, 0.5, -v86
	v_add_f32_e32 v84, v84, v100
	v_add_f32_e32 v85, v85, v101
	v_add_f32_e32 v81, v81, v89
	v_fma_f32 v87, v79, 0.5, -v87
	v_fma_f32 v88, v80, 0.5, -v88
	v_cvt_pk_bf16_f32 v80, v86, v87
	v_add_co_u32_e32 v86, vcc, s41, v182
	v_fma_f32 v84, v84, 0.5, -v100
	v_fma_f32 v85, v85, 0.5, -v101
	v_fma_f32 v81, v81, 0.5, -v89
	v_addc_co_u32_e32 v87, vcc, 0, v183, vcc
	global_load_dwordx4 v[102:105], v[102:103], off
	v_cvt_pk_bf16_f32 v79, v84, v85
	global_load_dwordx4 v[106:109], v[106:107], off
	v_cvt_pk_bf16_f32 v81, v88, v81
	global_load_dwordx4 v[82:85], v[82:83], off
	v_fma_f32 v98, v155, 0.5, -v98
	global_load_dwordx4 v[86:89], v[86:87], off
	v_fma_f32 v99, v156, 0.5, -v99
	v_cvt_pk_bf16_f32 v78, v98, v99
	s_add_u32 s6, s6, 64
	s_addc_u32 s7, s7, 0
	v_add_u32_e32 v96, 0x200, v96
	v_lshl_add_u64 v[90:91], v[90:91], 0, 64
	s_cmpk_lg_i32 s6, 0x200
	v_lshl_add_u64 v[92:93], v[92:93], 0, 32
	s_waitcnt vmcnt(3)
	v_mfma_f32_32x32x16_bf16 v[2:17], v[78:81], v[102:105], v[2:17]
	s_waitcnt vmcnt(2)
	v_mfma_f32_32x32x16_bf16 v[18:33], v[78:81], v[106:109], v[18:33]
	s_waitcnt vmcnt(1)
	v_mfma_f32_32x32x16_bf16 v[34:49], v[78:81], v[82:85], v[34:49]
	s_waitcnt vmcnt(0)
	v_mfma_f32_32x32x16_bf16 v[50:65], v[78:81], v[86:89], v[50:65]
	s_cbranch_scc0 .LBB0_468
	v_mov_b64_e32 v[80:81], v[76:77]
	v_mov_b64_e32 v[84:85], v[72:73]
	v_mov_b64_e32 v[88:89], v[68:69]
	v_mov_b64_e32 v[78:79], v[74:75]
	v_mov_b64_e32 v[82:83], v[70:71]
	v_mov_b64_e32 v[86:87], v[66:67]
	s_cmpk_eq_i32 s6, 0x1c0
	s_cbranch_scc0 .LBB0_465
	s_branch .LBB0_466

.LBB0_479:
	v_lshl_add_u64 v[90:91], s[10:11], 4, v[174:175]
	v_add_co_u32_e32 v82, vcc, 0x900000, v90
	s_mov_b32 s8, s46
	s_nop 0
	v_addc_co_u32_e32 v83, vcc, 0, v91, vcc
	v_add_co_u32_e32 v86, vcc, 0x902000, v90
	s_nop 1
	v_addc_co_u32_e32 v87, vcc, 0, v91, vcc
	v_add_co_u32_e32 v92, vcc, 0x904000, v90
	global_load_dwordx4 v[82:85], v[82:83], off offset:512
	s_nop 0
	global_load_dwordx4 v[86:89], v[86:87], off offset:512
	v_addc_co_u32_e32 v93, vcc, 0, v91, vcc
	v_add_co_u32_e32 v94, vcc, 0x906000, v90
	s_nop 1
	v_addc_co_u32_e32 v95, vcc, 0, v91, vcc
	global_load_dwordx4 v[90:93], v[92:93], off offset:512
	s_nop 0
	global_load_dwordx4 v[94:97], v[94:95], off offset:512

.LBB0_489:
	v_lshl_add_u64 v[100:101], v[90:91], 0, s[6:7]
	v_lshlrev_b32_e32 v96, 16, v86
	v_and_b32_e32 v97, 0xffff0000, v86
	v_lshlrev_b32_e32 v98, 16, v87
	v_and_b32_e32 v99, 0xffff0000, v87
	v_lshlrev_b32_e32 v86, 16, v88
	v_and_b32_e32 v87, 0xffff0000, v88
	v_add_co_u32_e32 v100, vcc, s34, v100
	v_lshlrev_b32_e32 v88, 16, v89
	v_and_b32_e32 v89, 0xffff0000, v89
	v_addc_co_u32_e32 v101, vcc, 0, v101, vcc
	v_add_f32_e32 v78, v78, v86
	v_add_f32_e32 v79, v79, v87
	global_store_dwordx4 v[100:101], v[96:99], off offset:512
	global_store_dwordx4 v[100:101], v[86:89], off offset:528
	s_lshl_b64 s[10:11], s[10:11], 5
	v_add_f32_e32 v84, v84, v98
	v_add_f32_e32 v80, v80, v88
	v_add_f32_e32 v85, v85, v99
	v_add_f32_e32 v81, v81, v89
	v_fma_f32 v86, v78, s42, -v86
	v_fma_f32 v87, v79, s42, -v87
	v_lshl_add_u64 v[100:101], v[122:123], 0, s[10:11]
	v_lshl_add_u64 v[104:105], v[124:125], 0, s[10:11]
	v_add_f32_e32 v108, v82, v96
	v_add_f32_e32 v109, v83, v97
	v_lshl_add_u64 v[82:83], v[126:127], 0, s[10:11]
	v_fma_f32 v84, v84, s42, -v98
	v_fma_f32 v85, v85, s42, -v99
	v_fma_f32 v88, v80, s42, -v88
	v_fma_f32 v81, v81, s42, -v89
	v_cvt_pk_bf16_f32 v80, v86, v87
	v_lshl_add_u64 v[86:87], v[128:129], 0, s[10:11]
	global_load_dwordx4 v[100:103], v[100:101], off
	v_cvt_pk_bf16_f32 v79, v84, v85
	global_load_dwordx4 v[104:107], v[104:105], off
	v_cvt_pk_bf16_f32 v81, v88, v81
	global_load_dwordx4 v[82:85], v[82:83], off
	v_fma_f32 v96, v108, s42, -v96
	global_load_dwordx4 v[86:89], v[86:87], off
	v_fma_f32 v97, v109, s42, -v97
	v_cvt_pk_bf16_f32 v78, v96, v97
	s_add_i32 s28, s28, 1
	s_add_u32 s6, s6, 64
	s_addc_u32 s7, s7, 0
	s_add_u32 s2, s2, 16
	s_addc_u32 s3, s3, 0
	s_cmpk_lg_i32 s6, 0x200
	v_lshl_add_u64 v[92:93], v[92:93], 0, 32
	s_waitcnt vmcnt(3)
	v_mfma_f32_32x32x16_bf16 v[2:17], v[78:81], v[100:103], v[2:17]
	s_waitcnt vmcnt(2)
	v_mfma_f32_32x32x16_bf16 v[18:33], v[78:81], v[104:107], v[18:33]
	s_waitcnt vmcnt(1)
	v_mfma_f32_32x32x16_bf16 v[34:49], v[78:81], v[82:85], v[34:49]
	s_waitcnt vmcnt(0)
	v_mfma_f32_32x32x16_bf16 v[50:65], v[78:81], v[86:89], v[50:65]
	s_cbranch_scc0 .LBB0_491
	v_mov_b64_e32 v[80:81], v[76:77]
	v_mov_b64_e32 v[84:85], v[72:73]
	v_mov_b64_e32 v[88:89], v[68:69]
	v_mov_b64_e32 v[78:79], v[74:75]
	v_mov_b64_e32 v[82:83], v[70:71]
	v_mov_b64_e32 v[86:87], v[66:67]
	s_cmpk_eq_i32 s6, 0x1c0
	s_mov_b64 s[10:11], s[2:3]
	s_cbranch_scc0 .LBB0_488
	s_branch .LBB0_489

.LBB0_502:
	v_lshl_add_u64 v[90:91], s[2:3], 4, v[174:175]
	v_add_co_u32_e32 v82, vcc, 0x908000, v90
	s_mov_b32 s8, s28
	s_nop 0
	v_addc_co_u32_e32 v83, vcc, 0, v91, vcc
	v_add_co_u32_e32 v86, vcc, 0x90a000, v90
	s_nop 1
	v_addc_co_u32_e32 v87, vcc, 0, v91, vcc
	v_add_co_u32_e32 v92, vcc, 0x90c000, v90
	global_load_dwordx4 v[82:85], v[82:83], off offset:512
	s_nop 0
	global_load_dwordx4 v[86:89], v[86:87], off offset:512
	v_addc_co_u32_e32 v93, vcc, 0, v91, vcc
	v_add_co_u32_e32 v94, vcc, 0x90e000, v90
	s_nop 1
	v_addc_co_u32_e32 v95, vcc, 0, v91, vcc
	global_load_dwordx4 v[90:93], v[92:93], off offset:512
	s_nop 0
	global_load_dwordx4 v[94:97], v[94:95], off offset:512
